# sel loop: per-tile row-max removed; lazy softmax reference move decided after the tile from its row sum (exact, reference-invariant), next-tile scores adjusted in the rare path
# speedup vs baseline: 1.0503x; 1.0160x over previous
.Lsel_nodiag_0b:
	v_add_u32_e32 v187, s81, v208
	ds_read_b128 v[124:127], v187 offset:9216
	ds_read_b128 v[144:147], v187 offset:13824
	ds_read_b128 v[148:151], v187 offset:9248
	v_exp_f32_e32 v80, v80
	v_exp_f32_e32 v81, v81
	v_exp_f32_e32 v82, v82
	v_exp_f32_e32 v83, v83
	s_waitcnt lgkmcnt(6)
	v_mfma_f32_32x32x16_bf16 v[238:253], v[108:111], v[128:131], v[2:17]
	ds_read_b128 v[108:111], v0 offset:64
	v_exp_f32_e32 v84, v84
	v_exp_f32_e32 v85, v85
	v_exp_f32_e32 v86, v86
	v_exp_f32_e32 v87, v87
	s_waitcnt lgkmcnt(6)
	v_mfma_f32_32x32x16_bf16 v[222:237], v[112:115], v[128:131], v[2:17]
	ds_read_b128 v[112:115], v0 offset:4672
	v_pk_add_f32 v[164:165], v[80:81], 0 op_sel_hi:[1,0]
	v_pk_add_f32 v[164:165], v[82:83], v[164:165]
	v_cvt_pk_bf16_f32 v80, v80, v81
	v_cvt_pk_bf16_f32 v81, v82, v83
	v_pk_add_f32 v[164:165], v[84:85], v[164:165]
	v_pk_add_f32 v[164:165], v[86:87], v[164:165]
	v_cvt_pk_bf16_f32 v82, v84, v85
	v_cvt_pk_bf16_f32 v83, v86, v87
	v_cndmask_b32_e64 v80, v80, 0, s[72:73]
	v_cndmask_b32_e64 v81, v81, 0, s[72:73]
	v_cndmask_b32_e64 v82, v82, 0, s[72:73]
	v_cndmask_b32_e64 v83, v83, 0, s[72:73]
	v_exp_f32_e32 v88, v88
	v_exp_f32_e32 v89, v89
	s_waitcnt lgkmcnt(4)
	v_mfma_f32_32x32x16_bf16 v[48:63], v[124:127], v[80:83], v[48:63]
	ds_read_b128 v[124:127], v187 offset:13856
	v_exp_f32_e32 v90, v90
	v_exp_f32_e32 v91, v91
	s_waitcnt lgkmcnt(4)
	v_mfma_f32_32x32x16_bf16 v[32:47], v[144:147], v[80:83], v[32:47]
	ds_read_b128 v[144:147], v187 offset:9280
	v_exp_f32_e32 v92, v92
	v_exp_f32_e32 v93, v93
	v_mfma_f32_32x32x16_bf16 v[238:253], v[116:119], v[132:135], v[238:253]
	ds_read_b128 v[116:119], v0 offset:96
	v_exp_f32_e32 v94, v94
	v_exp_f32_e32 v95, v95
	v_mfma_f32_32x32x16_bf16 v[222:237], v[120:123], v[132:135], v[222:237]
	ds_read_b128 v[120:123], v0 offset:4704
	v_pk_add_f32 v[164:165], v[88:89], v[164:165]
	v_pk_add_f32 v[164:165], v[90:91], v[164:165]
	v_cvt_pk_bf16_f32 v88, v88, v89
	v_cvt_pk_bf16_f32 v89, v90, v91
	v_pk_add_f32 v[164:165], v[92:93], v[164:165]
	v_pk_add_f32 v[164:165], v[94:95], v[164:165]
	v_cvt_pk_bf16_f32 v90, v92, v93
	v_cvt_pk_bf16_f32 v91, v94, v95
	v_cndmask_b32_e64 v88, v88, 0, s[72:73]
	v_cndmask_b32_e64 v89, v89, 0, s[72:73]
	v_cndmask_b32_e64 v90, v90, 0, s[72:73]
	v_cndmask_b32_e64 v91, v91, 0, s[72:73]
	v_exp_f32_e32 v64, v64
	v_exp_f32_e32 v65, v65
	s_waitcnt lgkmcnt(6)
	v_mfma_f32_32x32x16_bf16 v[48:63], v[148:151], v[88:91], v[48:63]
	ds_read_b128 v[148:151], v187 offset:13888
	v_exp_f32_e32 v66, v66
	v_exp_f32_e32 v67, v67
	s_waitcnt lgkmcnt(4)
	v_mfma_f32_32x32x16_bf16 v[32:47], v[124:127], v[88:91], v[32:47]
	ds_read_b128 v[124:127], v187 offset:9312
	v_exp_f32_e32 v68, v68
	v_exp_f32_e32 v69, v69
	v_mfma_f32_32x32x16_bf16 v[238:253], v[108:111], v[136:139], v[238:253]
	v_exp_f32_e32 v70, v70
	v_exp_f32_e32 v71, v71
	v_mfma_f32_32x32x16_bf16 v[222:237], v[112:115], v[136:139], v[222:237]
	v_pk_add_f32 v[164:165], v[64:65], v[164:165]
	v_pk_add_f32 v[164:165], v[66:67], v[164:165]
	v_cvt_pk_bf16_f32 v64, v64, v65
	v_cvt_pk_bf16_f32 v65, v66, v67
	v_pk_add_f32 v[164:165], v[68:69], v[164:165]
	v_pk_add_f32 v[164:165], v[70:71], v[164:165]
	v_cvt_pk_bf16_f32 v66, v68, v69
	v_cvt_pk_bf16_f32 v67, v70, v71
	v_cndmask_b32_e64 v64, v64, 0, s[72:73]
	v_cndmask_b32_e64 v65, v65, 0, s[72:73]
	v_cndmask_b32_e64 v66, v66, 0, s[72:73]
	v_cndmask_b32_e64 v67, v67, 0, s[72:73]
	v_exp_f32_e32 v72, v72
	v_exp_f32_e32 v73, v73
	s_waitcnt lgkmcnt(4)
	v_mfma_f32_32x32x16_bf16 v[48:63], v[144:147], v[64:67], v[48:63]
	ds_read_b128 v[144:147], v187 offset:13920
	v_exp_f32_e32 v74, v74
	v_exp_f32_e32 v75, v75
	s_waitcnt lgkmcnt(2)
	v_mfma_f32_32x32x16_bf16 v[32:47], v[148:151], v[64:67], v[32:47]
	v_exp_f32_e32 v76, v76
	v_exp_f32_e32 v77, v77
	v_mfma_f32_32x32x16_bf16 v[238:253], v[116:119], v[140:143], v[238:253]
	v_exp_f32_e32 v78, v78
	v_exp_f32_e32 v79, v79
	v_mfma_f32_32x32x16_bf16 v[222:237], v[120:123], v[140:143], v[222:237]
	v_pk_add_f32 v[164:165], v[72:73], v[164:165]
	v_pk_add_f32 v[164:165], v[74:75], v[164:165]
	v_cvt_pk_bf16_f32 v72, v72, v73
	v_cvt_pk_bf16_f32 v73, v74, v75
	v_pk_add_f32 v[164:165], v[76:77], v[164:165]
	v_pk_add_f32 v[164:165], v[78:79], v[164:165]
	v_cvt_pk_bf16_f32 v74, v76, v77
	v_cvt_pk_bf16_f32 v75, v78, v79
	v_cndmask_b32_e64 v72, v72, 0, s[72:73]
	v_cndmask_b32_e64 v73, v73, 0, s[72:73]
	v_cndmask_b32_e64 v74, v74, 0, s[72:73]
	v_cndmask_b32_e64 v75, v75, 0, s[72:73]
	s_nop 1
	s_waitcnt lgkmcnt(1)
	v_mfma_f32_32x32x16_bf16 v[48:63], v[124:127], v[72:75], v[48:63]
	s_waitcnt lgkmcnt(0)
	v_mfma_f32_32x32x16_bf16 v[32:47], v[144:147], v[72:75], v[32:47]
	v_add_f32_e32 v164, v164, v165
	v_cndmask_b32_e64 v164, v164, 0, s[72:73]
	v_add_f32_e32 v106, v106, v164
	v_cmp_lt_f32_e32 vcc, 0x43800000, v164
	s_cbranch_vccz .Lsel_noresc_0b
	s_nop 15
	s_nop 15
	v_mov_b32_e32 v107, v164
	s_nop 1
	v_permlane32_swap_b32_e32 v164, v107
	v_add_f32_e32 v164, v164, v107
	v_log_f32_e32 v160, v164
	s_nop 0
	v_max_f32_e32 v160, 0, v160
	v_exp_f32_e64 v162, -v160
	v_sub_f32_e32 v2, v2, v160
	v_sub_f32_e32 v3, v3, v160
	v_sub_f32_e32 v4, v4, v160
	v_sub_f32_e32 v5, v5, v160
	v_sub_f32_e32 v6, v6, v160
	v_sub_f32_e32 v7, v7, v160
	v_sub_f32_e32 v8, v8, v160
	v_sub_f32_e32 v9, v9, v160
	v_sub_f32_e32 v10, v10, v160
	v_sub_f32_e32 v11, v11, v160
	v_sub_f32_e32 v12, v12, v160
	v_sub_f32_e32 v13, v13, v160
	v_sub_f32_e32 v14, v14, v160
	v_sub_f32_e32 v15, v15, v160
	v_sub_f32_e32 v16, v16, v160
	v_sub_f32_e32 v17, v17, v160
	v_mul_f32_e32 v106, v106, v162
	v_pk_mul_f32 v[48:49], v[48:49], v[162:163] op_sel_hi:[1,0]
	v_pk_mul_f32 v[32:33], v[32:33], v[162:163] op_sel_hi:[1,0]
	v_pk_mul_f32 v[50:51], v[50:51], v[162:163] op_sel_hi:[1,0]
	v_pk_mul_f32 v[34:35], v[34:35], v[162:163] op_sel_hi:[1,0]
	v_pk_mul_f32 v[52:53], v[52:53], v[162:163] op_sel_hi:[1,0]
	v_pk_mul_f32 v[36:37], v[36:37], v[162:163] op_sel_hi:[1,0]
	v_pk_mul_f32 v[54:55], v[54:55], v[162:163] op_sel_hi:[1,0]
	v_pk_mul_f32 v[38:39], v[38:39], v[162:163] op_sel_hi:[1,0]
	v_pk_mul_f32 v[56:57], v[56:57], v[162:163] op_sel_hi:[1,0]
	v_pk_mul_f32 v[40:41], v[40:41], v[162:163] op_sel_hi:[1,0]
	v_pk_mul_f32 v[58:59], v[58:59], v[162:163] op_sel_hi:[1,0]
	v_pk_mul_f32 v[42:43], v[42:43], v[162:163] op_sel_hi:[1,0]
	v_pk_mul_f32 v[60:61], v[60:61], v[162:163] op_sel_hi:[1,0]
	v_pk_mul_f32 v[44:45], v[44:45], v[162:163] op_sel_hi:[1,0]
	v_pk_mul_f32 v[62:63], v[62:63], v[162:163] op_sel_hi:[1,0]
	v_pk_mul_f32 v[46:47], v[46:47], v[162:163] op_sel_hi:[1,0]
	v_pk_add_f32 v[238:239], v[238:239], v[160:161] op_sel_hi:[1,0] neg_lo:[0,1] neg_hi:[0,1]
	v_pk_add_f32 v[222:223], v[222:223], v[160:161] op_sel_hi:[1,0] neg_lo:[0,1] neg_hi:[0,1]
	v_pk_add_f32 v[240:241], v[240:241], v[160:161] op_sel_hi:[1,0] neg_lo:[0,1] neg_hi:[0,1]
	v_pk_add_f32 v[224:225], v[224:225], v[160:161] op_sel_hi:[1,0] neg_lo:[0,1] neg_hi:[0,1]
	v_pk_add_f32 v[242:243], v[242:243], v[160:161] op_sel_hi:[1,0] neg_lo:[0,1] neg_hi:[0,1]
	v_pk_add_f32 v[226:227], v[226:227], v[160:161] op_sel_hi:[1,0] neg_lo:[0,1] neg_hi:[0,1]
	v_pk_add_f32 v[244:245], v[244:245], v[160:161] op_sel_hi:[1,0] neg_lo:[0,1] neg_hi:[0,1]
	v_pk_add_f32 v[228:229], v[228:229], v[160:161] op_sel_hi:[1,0] neg_lo:[0,1] neg_hi:[0,1]
	v_pk_add_f32 v[246:247], v[246:247], v[160:161] op_sel_hi:[1,0] neg_lo:[0,1] neg_hi:[0,1]
	v_pk_add_f32 v[230:231], v[230:231], v[160:161] op_sel_hi:[1,0] neg_lo:[0,1] neg_hi:[0,1]
	v_pk_add_f32 v[248:249], v[248:249], v[160:161] op_sel_hi:[1,0] neg_lo:[0,1] neg_hi:[0,1]
	v_pk_add_f32 v[232:233], v[232:233], v[160:161] op_sel_hi:[1,0] neg_lo:[0,1] neg_hi:[0,1]
	v_pk_add_f32 v[250:251], v[250:251], v[160:161] op_sel_hi:[1,0] neg_lo:[0,1] neg_hi:[0,1]
	v_pk_add_f32 v[234:235], v[234:235], v[160:161] op_sel_hi:[1,0] neg_lo:[0,1] neg_hi:[0,1]
	v_pk_add_f32 v[252:253], v[252:253], v[160:161] op_sel_hi:[1,0] neg_lo:[0,1] neg_hi:[0,1]
	v_pk_add_f32 v[236:237], v[236:237], v[160:161] op_sel_hi:[1,0] neg_lo:[0,1] neg_hi:[0,1]
	s_nop 1
.Lsel_noresc_0b:
	s_branch .Lsel_tail_0
.Lsel_Nonly_0:
	v_add_u32_e32 v0, s82, v208
	ds_read_b128 v[108:111], v0
	ds_read_b128 v[112:115], v0 offset:4608
	ds_read_b128 v[116:119], v0 offset:32
	ds_read_b128 v[120:123], v0 offset:4640
	s_waitcnt lgkmcnt(3)
	v_mfma_f32_32x32x16_bf16 v[238:253], v[108:111], v[128:131], v[2:17]
	ds_read_b128 v[108:111], v0 offset:64
	s_waitcnt lgkmcnt(3)
	v_mfma_f32_32x32x16_bf16 v[222:237], v[112:115], v[128:131], v[2:17]
	ds_read_b128 v[112:115], v0 offset:4672
	s_waitcnt lgkmcnt(3)
	v_mfma_f32_32x32x16_bf16 v[238:253], v[116:119], v[132:135], v[238:253]
	ds_read_b128 v[116:119], v0 offset:96
	s_waitcnt lgkmcnt(3)
	v_mfma_f32_32x32x16_bf16 v[222:237], v[120:123], v[132:135], v[222:237]
	ds_read_b128 v[120:123], v0 offset:4704
	s_waitcnt lgkmcnt(3)
	v_mfma_f32_32x32x16_bf16 v[238:253], v[108:111], v[136:139], v[238:253]
	s_waitcnt lgkmcnt(2)
	v_mfma_f32_32x32x16_bf16 v[222:237], v[112:115], v[136:139], v[222:237]
	s_waitcnt lgkmcnt(1)
	v_mfma_f32_32x32x16_bf16 v[238:253], v[116:119], v[140:143], v[238:253]
	s_waitcnt lgkmcnt(0)
	v_mfma_f32_32x32x16_bf16 v[222:237], v[120:123], v[140:143], v[222:237]
	s_branch .Lsel_tail_0

.Lsel_nodiag_0c:
	v_add_u32_e32 v187, s81, v208
	ds_read_b128 v[124:127], v187 offset:9216
	ds_read_b128 v[144:147], v187 offset:13824
	ds_read_b128 v[148:151], v187 offset:9248
	v_exp_f32_e32 v80, v80
	v_exp_f32_e32 v81, v81
	v_exp_f32_e32 v82, v82
	v_exp_f32_e32 v83, v83
	v_exp_f32_e32 v84, v84
	v_exp_f32_e32 v85, v85
	v_exp_f32_e32 v86, v86
	v_exp_f32_e32 v87, v87
	v_pk_add_f32 v[164:165], v[80:81], 0 op_sel_hi:[1,0]
	v_pk_add_f32 v[164:165], v[82:83], v[164:165]
	v_cvt_pk_bf16_f32 v80, v80, v81
	v_cvt_pk_bf16_f32 v81, v82, v83
	v_pk_add_f32 v[164:165], v[84:85], v[164:165]
	v_pk_add_f32 v[164:165], v[86:87], v[164:165]
	v_cvt_pk_bf16_f32 v82, v84, v85
	v_cvt_pk_bf16_f32 v83, v86, v87
	v_cndmask_b32_e64 v80, v80, 0, s[72:73]
	v_cndmask_b32_e64 v81, v81, 0, s[72:73]
	v_cndmask_b32_e64 v82, v82, 0, s[72:73]
	v_cndmask_b32_e64 v83, v83, 0, s[72:73]
	v_exp_f32_e32 v88, v88
	v_exp_f32_e32 v89, v89
	s_waitcnt lgkmcnt(2)
	v_mfma_f32_32x32x16_bf16 v[48:63], v[124:127], v[80:83], v[48:63]
	ds_read_b128 v[124:127], v187 offset:13856
	v_exp_f32_e32 v90, v90
	v_exp_f32_e32 v91, v91
	s_waitcnt lgkmcnt(2)
	v_mfma_f32_32x32x16_bf16 v[32:47], v[144:147], v[80:83], v[32:47]
	ds_read_b128 v[144:147], v187 offset:9280
	v_exp_f32_e32 v92, v92
	v_exp_f32_e32 v93, v93
	v_exp_f32_e32 v94, v94
	v_exp_f32_e32 v95, v95
	v_pk_add_f32 v[164:165], v[88:89], v[164:165]
	v_pk_add_f32 v[164:165], v[90:91], v[164:165]
	v_cvt_pk_bf16_f32 v88, v88, v89
	v_cvt_pk_bf16_f32 v89, v90, v91
	v_pk_add_f32 v[164:165], v[92:93], v[164:165]
	v_pk_add_f32 v[164:165], v[94:95], v[164:165]
	v_cvt_pk_bf16_f32 v90, v92, v93
	v_cvt_pk_bf16_f32 v91, v94, v95
	v_cndmask_b32_e64 v88, v88, 0, s[72:73]
	v_cndmask_b32_e64 v89, v89, 0, s[72:73]
	v_cndmask_b32_e64 v90, v90, 0, s[72:73]
	v_cndmask_b32_e64 v91, v91, 0, s[72:73]
	v_exp_f32_e32 v64, v64
	v_exp_f32_e32 v65, v65
	s_waitcnt lgkmcnt(2)
	v_mfma_f32_32x32x16_bf16 v[48:63], v[148:151], v[88:91], v[48:63]
	ds_read_b128 v[148:151], v187 offset:13888
	v_exp_f32_e32 v66, v66
	v_exp_f32_e32 v67, v67
	s_waitcnt lgkmcnt(2)
	v_mfma_f32_32x32x16_bf16 v[32:47], v[124:127], v[88:91], v[32:47]
	ds_read_b128 v[124:127], v187 offset:9312
	v_exp_f32_e32 v68, v68
	v_exp_f32_e32 v69, v69
	v_exp_f32_e32 v70, v70
	v_exp_f32_e32 v71, v71
	v_pk_add_f32 v[164:165], v[64:65], v[164:165]
	v_pk_add_f32 v[164:165], v[66:67], v[164:165]
	v_cvt_pk_bf16_f32 v64, v64, v65
	v_cvt_pk_bf16_f32 v65, v66, v67
	v_pk_add_f32 v[164:165], v[68:69], v[164:165]
	v_pk_add_f32 v[164:165], v[70:71], v[164:165]
	v_cvt_pk_bf16_f32 v66, v68, v69
	v_cvt_pk_bf16_f32 v67, v70, v71
	v_cndmask_b32_e64 v64, v64, 0, s[72:73]
	v_cndmask_b32_e64 v65, v65, 0, s[72:73]
	v_cndmask_b32_e64 v66, v66, 0, s[72:73]
	v_cndmask_b32_e64 v67, v67, 0, s[72:73]
	v_exp_f32_e32 v72, v72
	v_exp_f32_e32 v73, v73
	s_waitcnt lgkmcnt(2)
	v_mfma_f32_32x32x16_bf16 v[48:63], v[144:147], v[64:67], v[48:63]
	ds_read_b128 v[144:147], v187 offset:13920
	v_exp_f32_e32 v74, v74
	v_exp_f32_e32 v75, v75
	s_waitcnt lgkmcnt(2)
	v_mfma_f32_32x32x16_bf16 v[32:47], v[148:151], v[64:67], v[32:47]
	v_exp_f32_e32 v76, v76
	v_exp_f32_e32 v77, v77
	v_exp_f32_e32 v78, v78
	v_exp_f32_e32 v79, v79
	v_pk_add_f32 v[164:165], v[72:73], v[164:165]
	v_pk_add_f32 v[164:165], v[74:75], v[164:165]
	v_cvt_pk_bf16_f32 v72, v72, v73
	v_cvt_pk_bf16_f32 v73, v74, v75
	v_pk_add_f32 v[164:165], v[76:77], v[164:165]
	v_pk_add_f32 v[164:165], v[78:79], v[164:165]
	v_cvt_pk_bf16_f32 v74, v76, v77
	v_cvt_pk_bf16_f32 v75, v78, v79
	v_cndmask_b32_e64 v72, v72, 0, s[72:73]
	v_cndmask_b32_e64 v73, v73, 0, s[72:73]
	v_cndmask_b32_e64 v74, v74, 0, s[72:73]
	v_cndmask_b32_e64 v75, v75, 0, s[72:73]
	s_nop 1
	s_waitcnt lgkmcnt(1)
	v_mfma_f32_32x32x16_bf16 v[48:63], v[124:127], v[72:75], v[48:63]
	s_waitcnt lgkmcnt(0)
	v_mfma_f32_32x32x16_bf16 v[32:47], v[144:147], v[72:75], v[32:47]
	v_add_f32_e32 v164, v164, v165
	v_cndmask_b32_e64 v164, v164, 0, s[72:73]
	v_add_f32_e32 v106, v106, v164
	v_cmp_lt_f32_e32 vcc, 0x43800000, v164
	s_cbranch_vccz .Lsel_noresc_0c
	s_nop 15
	s_nop 15
	v_mov_b32_e32 v107, v164
	s_nop 1
	v_permlane32_swap_b32_e32 v164, v107
	v_add_f32_e32 v164, v164, v107
	v_log_f32_e32 v160, v164
	s_nop 0
	v_max_f32_e32 v160, 0, v160
	v_exp_f32_e64 v162, -v160
	v_sub_f32_e32 v2, v2, v160
	v_sub_f32_e32 v3, v3, v160
	v_sub_f32_e32 v4, v4, v160
	v_sub_f32_e32 v5, v5, v160
	v_sub_f32_e32 v6, v6, v160
	v_sub_f32_e32 v7, v7, v160
	v_sub_f32_e32 v8, v8, v160
	v_sub_f32_e32 v9, v9, v160
	v_sub_f32_e32 v10, v10, v160
	v_sub_f32_e32 v11, v11, v160
	v_sub_f32_e32 v12, v12, v160
	v_sub_f32_e32 v13, v13, v160
	v_sub_f32_e32 v14, v14, v160
	v_sub_f32_e32 v15, v15, v160
	v_sub_f32_e32 v16, v16, v160
	v_sub_f32_e32 v17, v17, v160
	v_mul_f32_e32 v106, v106, v162
	v_pk_mul_f32 v[48:49], v[48:49], v[162:163] op_sel_hi:[1,0]
	v_pk_mul_f32 v[32:33], v[32:33], v[162:163] op_sel_hi:[1,0]
	v_pk_mul_f32 v[50:51], v[50:51], v[162:163] op_sel_hi:[1,0]
	v_pk_mul_f32 v[34:35], v[34:35], v[162:163] op_sel_hi:[1,0]
	v_pk_mul_f32 v[52:53], v[52:53], v[162:163] op_sel_hi:[1,0]
	v_pk_mul_f32 v[36:37], v[36:37], v[162:163] op_sel_hi:[1,0]
	v_pk_mul_f32 v[54:55], v[54:55], v[162:163] op_sel_hi:[1,0]
	v_pk_mul_f32 v[38:39], v[38:39], v[162:163] op_sel_hi:[1,0]
	v_pk_mul_f32 v[56:57], v[56:57], v[162:163] op_sel_hi:[1,0]
	v_pk_mul_f32 v[40:41], v[40:41], v[162:163] op_sel_hi:[1,0]
	v_pk_mul_f32 v[58:59], v[58:59], v[162:163] op_sel_hi:[1,0]
	v_pk_mul_f32 v[42:43], v[42:43], v[162:163] op_sel_hi:[1,0]
	v_pk_mul_f32 v[60:61], v[60:61], v[162:163] op_sel_hi:[1,0]
	v_pk_mul_f32 v[44:45], v[44:45], v[162:163] op_sel_hi:[1,0]
	v_pk_mul_f32 v[62:63], v[62:63], v[162:163] op_sel_hi:[1,0]
	v_pk_mul_f32 v[46:47], v[46:47], v[162:163] op_sel_hi:[1,0]
	s_nop 1
.Lsel_noresc_0c:
.Lsel_tail_0:
	s_waitcnt lgkmcnt(0)
	s_and_b32 s1, s86, 31
	v_bfe_u32 v184, v184, s1, 1
	v_cmp_eq_u32_e64 s[98:99], 0, v184
	v_mov_b32_e32 v0, s77
	ds_read_b32 v182, v0 offset:16
	s_add_u32 s1, s76, 2
	s_cmp_lt_u32 s1, s79
	s_cbranch_scc0 .Lsel_nost_0
	s_add_u32 s1, s76, 3
	s_cmp_lt_u32 s1, s79
	s_cbranch_scc1 .Lsel_st2_0
	s_waitcnt vmcnt(0)
	s_branch .Lsel_st_0

.Lsel_nodiag_1b:
	v_add_u32_e32 v187, s81, v208
	ds_read_b128 v[124:127], v187 offset:9216
	ds_read_b128 v[144:147], v187 offset:13824
	ds_read_b128 v[148:151], v187 offset:9248
	v_exp_f32_e32 v238, v238
	v_exp_f32_e32 v239, v239
	v_exp_f32_e32 v240, v240
	v_exp_f32_e32 v241, v241
	s_waitcnt lgkmcnt(6)
	v_mfma_f32_32x32x16_bf16 v[80:95], v[108:111], v[128:131], v[2:17]
	ds_read_b128 v[108:111], v0 offset:64
	v_exp_f32_e32 v242, v242
	v_exp_f32_e32 v243, v243
	v_exp_f32_e32 v244, v244
	v_exp_f32_e32 v245, v245
	s_waitcnt lgkmcnt(6)
	v_mfma_f32_32x32x16_bf16 v[64:79], v[112:115], v[128:131], v[2:17]
	ds_read_b128 v[112:115], v0 offset:4672
	v_pk_add_f32 v[164:165], v[238:239], 0 op_sel_hi:[1,0]
	v_pk_add_f32 v[164:165], v[240:241], v[164:165]
	v_cvt_pk_bf16_f32 v238, v238, v239
	v_cvt_pk_bf16_f32 v239, v240, v241
	v_pk_add_f32 v[164:165], v[242:243], v[164:165]
	v_pk_add_f32 v[164:165], v[244:245], v[164:165]
	v_cvt_pk_bf16_f32 v240, v242, v243
	v_cvt_pk_bf16_f32 v241, v244, v245
	v_cndmask_b32_e64 v238, v238, 0, s[72:73]
	v_cndmask_b32_e64 v239, v239, 0, s[72:73]
	v_cndmask_b32_e64 v240, v240, 0, s[72:73]
	v_cndmask_b32_e64 v241, v241, 0, s[72:73]
	v_exp_f32_e32 v246, v246
	v_exp_f32_e32 v247, v247
	s_waitcnt lgkmcnt(4)
	v_mfma_f32_32x32x16_bf16 v[48:63], v[124:127], v[238:241], v[48:63]
	ds_read_b128 v[124:127], v187 offset:13856
	v_exp_f32_e32 v248, v248
	v_exp_f32_e32 v249, v249
	s_waitcnt lgkmcnt(4)
	v_mfma_f32_32x32x16_bf16 v[32:47], v[144:147], v[238:241], v[32:47]
	ds_read_b128 v[144:147], v187 offset:9280
	v_exp_f32_e32 v250, v250
	v_exp_f32_e32 v251, v251
	v_mfma_f32_32x32x16_bf16 v[80:95], v[116:119], v[132:135], v[80:95]
	ds_read_b128 v[116:119], v0 offset:96
	v_exp_f32_e32 v252, v252
	v_exp_f32_e32 v253, v253
	v_mfma_f32_32x32x16_bf16 v[64:79], v[120:123], v[132:135], v[64:79]
	ds_read_b128 v[120:123], v0 offset:4704
	v_pk_add_f32 v[164:165], v[246:247], v[164:165]
	v_pk_add_f32 v[164:165], v[248:249], v[164:165]
	v_cvt_pk_bf16_f32 v246, v246, v247
	v_cvt_pk_bf16_f32 v247, v248, v249
	v_pk_add_f32 v[164:165], v[250:251], v[164:165]
	v_pk_add_f32 v[164:165], v[252:253], v[164:165]
	v_cvt_pk_bf16_f32 v248, v250, v251
	v_cvt_pk_bf16_f32 v249, v252, v253
	v_cndmask_b32_e64 v246, v246, 0, s[72:73]
	v_cndmask_b32_e64 v247, v247, 0, s[72:73]
	v_cndmask_b32_e64 v248, v248, 0, s[72:73]
	v_cndmask_b32_e64 v249, v249, 0, s[72:73]
	v_exp_f32_e32 v222, v222
	v_exp_f32_e32 v223, v223
	s_waitcnt lgkmcnt(6)
	v_mfma_f32_32x32x16_bf16 v[48:63], v[148:151], v[246:249], v[48:63]
	ds_read_b128 v[148:151], v187 offset:13888
	v_exp_f32_e32 v224, v224
	v_exp_f32_e32 v225, v225
	s_waitcnt lgkmcnt(4)
	v_mfma_f32_32x32x16_bf16 v[32:47], v[124:127], v[246:249], v[32:47]
	ds_read_b128 v[124:127], v187 offset:9312
	v_exp_f32_e32 v226, v226
	v_exp_f32_e32 v227, v227
	v_mfma_f32_32x32x16_bf16 v[80:95], v[108:111], v[136:139], v[80:95]
	v_exp_f32_e32 v228, v228
	v_exp_f32_e32 v229, v229
	v_mfma_f32_32x32x16_bf16 v[64:79], v[112:115], v[136:139], v[64:79]
	v_pk_add_f32 v[164:165], v[222:223], v[164:165]
	v_pk_add_f32 v[164:165], v[224:225], v[164:165]
	v_cvt_pk_bf16_f32 v222, v222, v223
	v_cvt_pk_bf16_f32 v223, v224, v225
	v_pk_add_f32 v[164:165], v[226:227], v[164:165]
	v_pk_add_f32 v[164:165], v[228:229], v[164:165]
	v_cvt_pk_bf16_f32 v224, v226, v227
	v_cvt_pk_bf16_f32 v225, v228, v229
	v_cndmask_b32_e64 v222, v222, 0, s[72:73]
	v_cndmask_b32_e64 v223, v223, 0, s[72:73]
	v_cndmask_b32_e64 v224, v224, 0, s[72:73]
	v_cndmask_b32_e64 v225, v225, 0, s[72:73]
	v_exp_f32_e32 v230, v230
	v_exp_f32_e32 v231, v231
	s_waitcnt lgkmcnt(4)
	v_mfma_f32_32x32x16_bf16 v[48:63], v[144:147], v[222:225], v[48:63]
	ds_read_b128 v[144:147], v187 offset:13920
	v_exp_f32_e32 v232, v232
	v_exp_f32_e32 v233, v233
	s_waitcnt lgkmcnt(2)
	v_mfma_f32_32x32x16_bf16 v[32:47], v[148:151], v[222:225], v[32:47]
	v_exp_f32_e32 v234, v234
	v_exp_f32_e32 v235, v235
	v_mfma_f32_32x32x16_bf16 v[80:95], v[116:119], v[140:143], v[80:95]
	v_exp_f32_e32 v236, v236
	v_exp_f32_e32 v237, v237
	v_mfma_f32_32x32x16_bf16 v[64:79], v[120:123], v[140:143], v[64:79]
	v_pk_add_f32 v[164:165], v[230:231], v[164:165]
	v_pk_add_f32 v[164:165], v[232:233], v[164:165]
	v_cvt_pk_bf16_f32 v230, v230, v231
	v_cvt_pk_bf16_f32 v231, v232, v233
	v_pk_add_f32 v[164:165], v[234:235], v[164:165]
	v_pk_add_f32 v[164:165], v[236:237], v[164:165]
	v_cvt_pk_bf16_f32 v232, v234, v235
	v_cvt_pk_bf16_f32 v233, v236, v237
	v_cndmask_b32_e64 v230, v230, 0, s[72:73]
	v_cndmask_b32_e64 v231, v231, 0, s[72:73]
	v_cndmask_b32_e64 v232, v232, 0, s[72:73]
	v_cndmask_b32_e64 v233, v233, 0, s[72:73]
	s_nop 1
	s_waitcnt lgkmcnt(1)
	v_mfma_f32_32x32x16_bf16 v[48:63], v[124:127], v[230:233], v[48:63]
	s_waitcnt lgkmcnt(0)
	v_mfma_f32_32x32x16_bf16 v[32:47], v[144:147], v[230:233], v[32:47]
	v_add_f32_e32 v164, v164, v165
	v_cndmask_b32_e64 v164, v164, 0, s[72:73]
	v_add_f32_e32 v106, v106, v164
	v_cmp_lt_f32_e32 vcc, 0x43800000, v164
	s_cbranch_vccz .Lsel_noresc_1b
	s_nop 15
	s_nop 15
	v_mov_b32_e32 v107, v164
	s_nop 1
	v_permlane32_swap_b32_e32 v164, v107
	v_add_f32_e32 v164, v164, v107
	v_log_f32_e32 v160, v164
	s_nop 0
	v_max_f32_e32 v160, 0, v160
	v_exp_f32_e64 v162, -v160
	v_sub_f32_e32 v2, v2, v160
	v_sub_f32_e32 v3, v3, v160
	v_sub_f32_e32 v4, v4, v160
	v_sub_f32_e32 v5, v5, v160
	v_sub_f32_e32 v6, v6, v160
	v_sub_f32_e32 v7, v7, v160
	v_sub_f32_e32 v8, v8, v160
	v_sub_f32_e32 v9, v9, v160
	v_sub_f32_e32 v10, v10, v160
	v_sub_f32_e32 v11, v11, v160
	v_sub_f32_e32 v12, v12, v160
	v_sub_f32_e32 v13, v13, v160
	v_sub_f32_e32 v14, v14, v160
	v_sub_f32_e32 v15, v15, v160
	v_sub_f32_e32 v16, v16, v160
	v_sub_f32_e32 v17, v17, v160
	v_mul_f32_e32 v106, v106, v162
	v_pk_mul_f32 v[48:49], v[48:49], v[162:163] op_sel_hi:[1,0]
	v_pk_mul_f32 v[32:33], v[32:33], v[162:163] op_sel_hi:[1,0]
	v_pk_mul_f32 v[50:51], v[50:51], v[162:163] op_sel_hi:[1,0]
	v_pk_mul_f32 v[34:35], v[34:35], v[162:163] op_sel_hi:[1,0]
	v_pk_mul_f32 v[52:53], v[52:53], v[162:163] op_sel_hi:[1,0]
	v_pk_mul_f32 v[36:37], v[36:37], v[162:163] op_sel_hi:[1,0]
	v_pk_mul_f32 v[54:55], v[54:55], v[162:163] op_sel_hi:[1,0]
	v_pk_mul_f32 v[38:39], v[38:39], v[162:163] op_sel_hi:[1,0]
	v_pk_mul_f32 v[56:57], v[56:57], v[162:163] op_sel_hi:[1,0]
	v_pk_mul_f32 v[40:41], v[40:41], v[162:163] op_sel_hi:[1,0]
	v_pk_mul_f32 v[58:59], v[58:59], v[162:163] op_sel_hi:[1,0]
	v_pk_mul_f32 v[42:43], v[42:43], v[162:163] op_sel_hi:[1,0]
	v_pk_mul_f32 v[60:61], v[60:61], v[162:163] op_sel_hi:[1,0]
	v_pk_mul_f32 v[44:45], v[44:45], v[162:163] op_sel_hi:[1,0]
	v_pk_mul_f32 v[62:63], v[62:63], v[162:163] op_sel_hi:[1,0]
	v_pk_mul_f32 v[46:47], v[46:47], v[162:163] op_sel_hi:[1,0]
	v_pk_add_f32 v[80:81], v[80:81], v[160:161] op_sel_hi:[1,0] neg_lo:[0,1] neg_hi:[0,1]
	v_pk_add_f32 v[64:65], v[64:65], v[160:161] op_sel_hi:[1,0] neg_lo:[0,1] neg_hi:[0,1]
	v_pk_add_f32 v[82:83], v[82:83], v[160:161] op_sel_hi:[1,0] neg_lo:[0,1] neg_hi:[0,1]
	v_pk_add_f32 v[66:67], v[66:67], v[160:161] op_sel_hi:[1,0] neg_lo:[0,1] neg_hi:[0,1]
	v_pk_add_f32 v[84:85], v[84:85], v[160:161] op_sel_hi:[1,0] neg_lo:[0,1] neg_hi:[0,1]
	v_pk_add_f32 v[68:69], v[68:69], v[160:161] op_sel_hi:[1,0] neg_lo:[0,1] neg_hi:[0,1]
	v_pk_add_f32 v[86:87], v[86:87], v[160:161] op_sel_hi:[1,0] neg_lo:[0,1] neg_hi:[0,1]
	v_pk_add_f32 v[70:71], v[70:71], v[160:161] op_sel_hi:[1,0] neg_lo:[0,1] neg_hi:[0,1]
	v_pk_add_f32 v[88:89], v[88:89], v[160:161] op_sel_hi:[1,0] neg_lo:[0,1] neg_hi:[0,1]
	v_pk_add_f32 v[72:73], v[72:73], v[160:161] op_sel_hi:[1,0] neg_lo:[0,1] neg_hi:[0,1]
	v_pk_add_f32 v[90:91], v[90:91], v[160:161] op_sel_hi:[1,0] neg_lo:[0,1] neg_hi:[0,1]
	v_pk_add_f32 v[74:75], v[74:75], v[160:161] op_sel_hi:[1,0] neg_lo:[0,1] neg_hi:[0,1]
	v_pk_add_f32 v[92:93], v[92:93], v[160:161] op_sel_hi:[1,0] neg_lo:[0,1] neg_hi:[0,1]
	v_pk_add_f32 v[76:77], v[76:77], v[160:161] op_sel_hi:[1,0] neg_lo:[0,1] neg_hi:[0,1]
	v_pk_add_f32 v[94:95], v[94:95], v[160:161] op_sel_hi:[1,0] neg_lo:[0,1] neg_hi:[0,1]
	v_pk_add_f32 v[78:79], v[78:79], v[160:161] op_sel_hi:[1,0] neg_lo:[0,1] neg_hi:[0,1]
	s_nop 1
.Lsel_noresc_1b:
	s_branch .Lsel_tail_1
.Lsel_Nonly_1:
	v_add_u32_e32 v0, s82, v208
	ds_read_b128 v[108:111], v0
	ds_read_b128 v[112:115], v0 offset:4608
	ds_read_b128 v[116:119], v0 offset:32
	ds_read_b128 v[120:123], v0 offset:4640
	s_waitcnt lgkmcnt(3)
	v_mfma_f32_32x32x16_bf16 v[80:95], v[108:111], v[128:131], v[2:17]
	ds_read_b128 v[108:111], v0 offset:64
	s_waitcnt lgkmcnt(3)
	v_mfma_f32_32x32x16_bf16 v[64:79], v[112:115], v[128:131], v[2:17]
	ds_read_b128 v[112:115], v0 offset:4672
	s_waitcnt lgkmcnt(3)
	v_mfma_f32_32x32x16_bf16 v[80:95], v[116:119], v[132:135], v[80:95]
	ds_read_b128 v[116:119], v0 offset:96
	s_waitcnt lgkmcnt(3)
	v_mfma_f32_32x32x16_bf16 v[64:79], v[120:123], v[132:135], v[64:79]
	ds_read_b128 v[120:123], v0 offset:4704
	s_waitcnt lgkmcnt(3)
	v_mfma_f32_32x32x16_bf16 v[80:95], v[108:111], v[136:139], v[80:95]
	s_waitcnt lgkmcnt(2)
	v_mfma_f32_32x32x16_bf16 v[64:79], v[112:115], v[136:139], v[64:79]
	s_waitcnt lgkmcnt(1)
	v_mfma_f32_32x32x16_bf16 v[80:95], v[116:119], v[140:143], v[80:95]
	s_waitcnt lgkmcnt(0)
	v_mfma_f32_32x32x16_bf16 v[64:79], v[120:123], v[140:143], v[64:79]
	s_branch .Lsel_tail_1

.Lsel_nodiag_1c:
	v_add_u32_e32 v187, s81, v208
	ds_read_b128 v[124:127], v187 offset:9216
	ds_read_b128 v[144:147], v187 offset:13824
	ds_read_b128 v[148:151], v187 offset:9248
	v_exp_f32_e32 v238, v238
	v_exp_f32_e32 v239, v239
	v_exp_f32_e32 v240, v240
	v_exp_f32_e32 v241, v241
	v_exp_f32_e32 v242, v242
	v_exp_f32_e32 v243, v243
	v_exp_f32_e32 v244, v244
	v_exp_f32_e32 v245, v245
	v_pk_add_f32 v[164:165], v[238:239], 0 op_sel_hi:[1,0]
	v_pk_add_f32 v[164:165], v[240:241], v[164:165]
	v_cvt_pk_bf16_f32 v238, v238, v239
	v_cvt_pk_bf16_f32 v239, v240, v241
	v_pk_add_f32 v[164:165], v[242:243], v[164:165]
	v_pk_add_f32 v[164:165], v[244:245], v[164:165]
	v_cvt_pk_bf16_f32 v240, v242, v243
	v_cvt_pk_bf16_f32 v241, v244, v245
	v_cndmask_b32_e64 v238, v238, 0, s[72:73]
	v_cndmask_b32_e64 v239, v239, 0, s[72:73]
	v_cndmask_b32_e64 v240, v240, 0, s[72:73]
	v_cndmask_b32_e64 v241, v241, 0, s[72:73]
	v_exp_f32_e32 v246, v246
	v_exp_f32_e32 v247, v247
	s_waitcnt lgkmcnt(2)
	v_mfma_f32_32x32x16_bf16 v[48:63], v[124:127], v[238:241], v[48:63]
	ds_read_b128 v[124:127], v187 offset:13856
	v_exp_f32_e32 v248, v248
	v_exp_f32_e32 v249, v249
	s_waitcnt lgkmcnt(2)
	v_mfma_f32_32x32x16_bf16 v[32:47], v[144:147], v[238:241], v[32:47]
	ds_read_b128 v[144:147], v187 offset:9280
	v_exp_f32_e32 v250, v250
	v_exp_f32_e32 v251, v251
	v_exp_f32_e32 v252, v252
	v_exp_f32_e32 v253, v253
	v_pk_add_f32 v[164:165], v[246:247], v[164:165]
	v_pk_add_f32 v[164:165], v[248:249], v[164:165]
	v_cvt_pk_bf16_f32 v246, v246, v247
	v_cvt_pk_bf16_f32 v247, v248, v249
	v_pk_add_f32 v[164:165], v[250:251], v[164:165]
	v_pk_add_f32 v[164:165], v[252:253], v[164:165]
	v_cvt_pk_bf16_f32 v248, v250, v251
	v_cvt_pk_bf16_f32 v249, v252, v253
	v_cndmask_b32_e64 v246, v246, 0, s[72:73]
	v_cndmask_b32_e64 v247, v247, 0, s[72:73]
	v_cndmask_b32_e64 v248, v248, 0, s[72:73]
	v_cndmask_b32_e64 v249, v249, 0, s[72:73]
	v_exp_f32_e32 v222, v222
	v_exp_f32_e32 v223, v223
	s_waitcnt lgkmcnt(2)
	v_mfma_f32_32x32x16_bf16 v[48:63], v[148:151], v[246:249], v[48:63]
	ds_read_b128 v[148:151], v187 offset:13888
	v_exp_f32_e32 v224, v224
	v_exp_f32_e32 v225, v225
	s_waitcnt lgkmcnt(2)
	v_mfma_f32_32x32x16_bf16 v[32:47], v[124:127], v[246:249], v[32:47]
	ds_read_b128 v[124:127], v187 offset:9312
	v_exp_f32_e32 v226, v226
	v_exp_f32_e32 v227, v227
	v_exp_f32_e32 v228, v228
	v_exp_f32_e32 v229, v229
	v_pk_add_f32 v[164:165], v[222:223], v[164:165]
	v_pk_add_f32 v[164:165], v[224:225], v[164:165]
	v_cvt_pk_bf16_f32 v222, v222, v223
	v_cvt_pk_bf16_f32 v223, v224, v225
	v_pk_add_f32 v[164:165], v[226:227], v[164:165]
	v_pk_add_f32 v[164:165], v[228:229], v[164:165]
	v_cvt_pk_bf16_f32 v224, v226, v227
	v_cvt_pk_bf16_f32 v225, v228, v229
	v_cndmask_b32_e64 v222, v222, 0, s[72:73]
	v_cndmask_b32_e64 v223, v223, 0, s[72:73]
	v_cndmask_b32_e64 v224, v224, 0, s[72:73]
	v_cndmask_b32_e64 v225, v225, 0, s[72:73]
	v_exp_f32_e32 v230, v230
	v_exp_f32_e32 v231, v231
	s_waitcnt lgkmcnt(2)
	v_mfma_f32_32x32x16_bf16 v[48:63], v[144:147], v[222:225], v[48:63]
	ds_read_b128 v[144:147], v187 offset:13920
	v_exp_f32_e32 v232, v232
	v_exp_f32_e32 v233, v233
	s_waitcnt lgkmcnt(2)
	v_mfma_f32_32x32x16_bf16 v[32:47], v[148:151], v[222:225], v[32:47]
	v_exp_f32_e32 v234, v234
	v_exp_f32_e32 v235, v235
	v_exp_f32_e32 v236, v236
	v_exp_f32_e32 v237, v237
	v_pk_add_f32 v[164:165], v[230:231], v[164:165]
	v_pk_add_f32 v[164:165], v[232:233], v[164:165]
	v_cvt_pk_bf16_f32 v230, v230, v231
	v_cvt_pk_bf16_f32 v231, v232, v233
	v_pk_add_f32 v[164:165], v[234:235], v[164:165]
	v_pk_add_f32 v[164:165], v[236:237], v[164:165]
	v_cvt_pk_bf16_f32 v232, v234, v235
	v_cvt_pk_bf16_f32 v233, v236, v237
	v_cndmask_b32_e64 v230, v230, 0, s[72:73]
	v_cndmask_b32_e64 v231, v231, 0, s[72:73]
	v_cndmask_b32_e64 v232, v232, 0, s[72:73]
	v_cndmask_b32_e64 v233, v233, 0, s[72:73]
	s_nop 1
	s_waitcnt lgkmcnt(1)
	v_mfma_f32_32x32x16_bf16 v[48:63], v[124:127], v[230:233], v[48:63]
	s_waitcnt lgkmcnt(0)
	v_mfma_f32_32x32x16_bf16 v[32:47], v[144:147], v[230:233], v[32:47]
	v_add_f32_e32 v164, v164, v165
	v_cndmask_b32_e64 v164, v164, 0, s[72:73]
	v_add_f32_e32 v106, v106, v164
	v_cmp_lt_f32_e32 vcc, 0x43800000, v164
	s_cbranch_vccz .Lsel_noresc_1c
	s_nop 15
	s_nop 15
	v_mov_b32_e32 v107, v164
	s_nop 1
	v_permlane32_swap_b32_e32 v164, v107
	v_add_f32_e32 v164, v164, v107
	v_log_f32_e32 v160, v164
	s_nop 0
	v_max_f32_e32 v160, 0, v160
	v_exp_f32_e64 v162, -v160
	v_sub_f32_e32 v2, v2, v160
	v_sub_f32_e32 v3, v3, v160
	v_sub_f32_e32 v4, v4, v160
	v_sub_f32_e32 v5, v5, v160
	v_sub_f32_e32 v6, v6, v160
	v_sub_f32_e32 v7, v7, v160
	v_sub_f32_e32 v8, v8, v160
	v_sub_f32_e32 v9, v9, v160
	v_sub_f32_e32 v10, v10, v160
	v_sub_f32_e32 v11, v11, v160
	v_sub_f32_e32 v12, v12, v160
	v_sub_f32_e32 v13, v13, v160
	v_sub_f32_e32 v14, v14, v160
	v_sub_f32_e32 v15, v15, v160
	v_sub_f32_e32 v16, v16, v160
	v_sub_f32_e32 v17, v17, v160
	v_mul_f32_e32 v106, v106, v162
	v_pk_mul_f32 v[48:49], v[48:49], v[162:163] op_sel_hi:[1,0]
	v_pk_mul_f32 v[32:33], v[32:33], v[162:163] op_sel_hi:[1,0]
	v_pk_mul_f32 v[50:51], v[50:51], v[162:163] op_sel_hi:[1,0]
	v_pk_mul_f32 v[34:35], v[34:35], v[162:163] op_sel_hi:[1,0]
	v_pk_mul_f32 v[52:53], v[52:53], v[162:163] op_sel_hi:[1,0]
	v_pk_mul_f32 v[36:37], v[36:37], v[162:163] op_sel_hi:[1,0]
	v_pk_mul_f32 v[54:55], v[54:55], v[162:163] op_sel_hi:[1,0]
	v_pk_mul_f32 v[38:39], v[38:39], v[162:163] op_sel_hi:[1,0]
	v_pk_mul_f32 v[56:57], v[56:57], v[162:163] op_sel_hi:[1,0]
	v_pk_mul_f32 v[40:41], v[40:41], v[162:163] op_sel_hi:[1,0]
	v_pk_mul_f32 v[58:59], v[58:59], v[162:163] op_sel_hi:[1,0]
	v_pk_mul_f32 v[42:43], v[42:43], v[162:163] op_sel_hi:[1,0]
	v_pk_mul_f32 v[60:61], v[60:61], v[162:163] op_sel_hi:[1,0]
	v_pk_mul_f32 v[44:45], v[44:45], v[162:163] op_sel_hi:[1,0]
	v_pk_mul_f32 v[62:63], v[62:63], v[162:163] op_sel_hi:[1,0]
	v_pk_mul_f32 v[46:47], v[46:47], v[162:163] op_sel_hi:[1,0]
	s_nop 1
